# E31: E27 + RMSNorm row reductions use DPP quad_perm/row mirrors and permlane16/32 swaps instead of six ds_bpermute round trips (same butterfly order, bit-identical)
# speedup vs baseline: 1.0010x; 1.0010x over previous
; #define LAS __attribute__((address_space(3)))
; __device__ __forceinline__ unsigned cvt_pk_bf16(float lo, float hi) { f32x2_c v = {lo, hi}; bf16x2_c b = __builtin_convertvector(v, bf16x2_c); return __builtin_bit_cast(unsigned, b); }
; __device__ __forceinline__ float wave_sum(float v) {
; #pragma unroll
;     for (int o = 1; o < 64; o <<= 1) v += __shfl_xor(v, o);
;     return v;
; }
; __global__ void __launch_bounds__(NWAVES * 64, 2) mk_fwd(Args args) {
;     ...
;             for (int m = gw; m < SEQ; m += NGW) {
;                 const f32x4* xr = (const f32x4*)(xcur + (size_t)m * DMODEL) + lane;
;                 f32x4 v[8]; float s = 0.f;
; #pragma unroll
;                 for (int j = 0; j < 8; ++j) { v[j] = xr[64 * j]; s += (v[j][0] * v[j][0] + v[j][1] * v[j][1]) + (v[j][2] * v[j][2] + v[j][3] * v[j][3]); }
;                 const float rstd = __builtin_amdgcn_rsqf(wave_sum(s) * (1.f / DMODEL) + EPS);
;                 u32x2* o8 = (u32x2*)(Hb + (size_t)m * DMODEL) + lane;
; #pragma unroll
;                 for (int j = 0; j < 8; ++j) { const f32x4 g = *(const LAS f32x4*)(gL + 4 * lane + 256 * j), sh = *(const LAS f32x4*)(sL + 4 * lane + 256 * j);
;                     const f32x4 y = v[j] * rstd * g + sh; u32x2 w; w.x = cvt_pk_bf16(y[0], y[1]); w.y = cvt_pk_bf16(y[2], y[3]); o8[64 * j] = w; }
.Lnorm_nopf:
	v_mov_b32_e32 v108, v69
	v_mov_b32_e32 v109, v65
	v_mov_b32_e32 v112, v71
	v_mov_b32_e32 v113, v67
	v_mov_b32_e32 v106, v68
	v_mov_b32_e32 v107, v64
	v_mov_b32_e32 v110, v70
	v_mov_b32_e32 v111, v66
	v_pk_mul_f32 v[114:115], v[74:75], v[74:75]
	v_pk_mul_f32 v[116:117], v[72:73], v[72:73]
	v_pk_mul_f32 v[108:109], v[108:109], v[108:109]
	v_pk_mul_f32 v[112:113], v[112:113], v[112:113]
	v_pk_mov_b32 v[130:131], v[116:117], v[114:115] op_sel:[1,0]
	v_mov_b32_e32 v117, v115
	v_pk_fma_f32 v[106:107], v[106:107], v[106:107], v[108:109]
	v_pk_fma_f32 v[108:109], v[110:111], v[110:111], v[112:113]
	v_mul_f32_e32 v118, v81, v81
	v_mul_f32_e32 v120, v83, v83
	v_pk_add_f32 v[110:111], v[130:131], v[116:117]
	v_pk_add_f32 v[106:107], v[106:107], v[108:109]
	v_mul_f32_e32 v129, v76, v76
	v_mul_f32_e32 v132, v77, v77
	v_mul_f32_e32 v133, v78, v78
	v_mul_f32_e32 v134, v79, v79
	v_pk_fma_f32 v[114:115], v[80:81], v[80:81], v[118:119] op_sel_hi:[1,1,0]
	v_pk_fma_f32 v[118:119], v[82:83], v[82:83], v[120:121] op_sel_hi:[1,1,0]
	v_pk_add_f32 v[108:109], v[110:111], v[110:111] op_sel:[0,1] op_sel_hi:[1,0]
	v_pk_add_f32 v[106:107], v[106:107], v[106:107] op_sel:[0,1] op_sel_hi:[1,0]
	v_pk_mul_f32 v[122:123], v[86:87], v[86:87]
	v_pk_mul_f32 v[124:125], v[84:85], v[84:85]
	v_mov_b32_e32 v115, v133
	v_mov_b32_e32 v119, v134
	v_mov_b32_e32 v109, v132
	v_mov_b32_e32 v107, v129
	v_pk_mov_b32 v[120:121], v[124:125], v[122:123] op_sel:[1,0]
	v_mov_b32_e32 v125, v123
	v_pk_add_f32 v[110:111], v[114:115], v[118:119]
	v_pk_add_f32 v[106:107], v[106:107], v[108:109]
	v_mul_f32_e32 v126, v93, v93
	v_mul_f32_e32 v128, v95, v95
	v_pk_add_f32 v[112:113], v[120:121], v[124:125]
	v_pk_add_f32 v[106:107], v[106:107], v[110:111]
	v_mul_f32_e32 v135, v88, v88
	v_mul_f32_e32 v136, v89, v89
	v_mul_f32_e32 v137, v90, v90
	v_mul_f32_e32 v138, v91, v91
	v_pk_fma_f32 v[122:123], v[92:93], v[92:93], v[126:127] op_sel_hi:[1,1,0]
	v_pk_fma_f32 v[126:127], v[94:95], v[94:95], v[128:129] op_sel_hi:[1,1,0]
	v_pk_add_f32 v[112:113], v[112:113], v[112:113] op_sel:[0,1] op_sel_hi:[1,0]
	v_pk_add_f32 v[106:107], v[106:107], v[106:107] op_sel:[0,1] op_sel_hi:[1,0]
	v_mov_b32_e32 v123, v137
	v_mov_b32_e32 v127, v138
	v_mov_b32_e32 v113, v136
	v_mov_b32_e32 v107, v135
	v_pk_add_f32 v[114:115], v[122:123], v[126:127]
	v_pk_add_f32 v[106:107], v[106:107], v[112:113]
	s_nop 0
	v_pk_add_f32 v[106:107], v[106:107], v[114:115]
	s_nop 0
	v_add_f32_e32 v106, v106, v107
	s_waitcnt lgkmcnt(0)
	s_nop 1
	v_add_f32_dpp v106, v106, v106 quad_perm:[1,0,3,2] row_mask:0xf bank_mask:0xf
	s_nop 1
	v_add_f32_dpp v106, v106, v106 quad_perm:[2,3,0,1] row_mask:0xf bank_mask:0xf
	s_nop 1
	v_add_f32_dpp v106, v106, v106 row_half_mirror row_mask:0xf bank_mask:0xf
	s_nop 1
	v_add_f32_dpp v106, v106, v106 row_mirror row_mask:0xf bank_mask:0xf
	v_mov_b32_e32 v107, v106
	s_nop 1
	v_permlane16_swap_b32_e32 v106, v107
	v_add_f32_e32 v106, v106, v107
	v_mov_b32_e32 v107, v106
	s_nop 1
	v_permlane32_swap_b32_e32 v106, v107
	v_add_f32_e32 v106, v106, v107
	s_nop 0
	s_nop 0
	s_nop 0
	v_fmamk_f32 v106, v106, 0x3a000000, v253
	v_rsq_f32_e32 v106, v106
	s_nop 0
	v_pk_mul_f32 v[68:69], v[106:107], v[68:69] op_sel_hi:[0,1]
	v_pk_mul_f32 v[70:71], v[106:107], v[70:71] op_sel_hi:[0,1]
	v_pk_mul_f32 v[64:65], v[106:107], v[64:65] op_sel_hi:[0,1]
	v_pk_mul_f32 v[66:67], v[106:107], v[66:67] op_sel_hi:[0,1]
	v_pk_mul_f32 v[72:73], v[106:107], v[72:73] op_sel_hi:[0,1]
	v_pk_mul_f32 v[74:75], v[106:107], v[74:75] op_sel_hi:[0,1]
	v_pk_mul_f32 v[80:81], v[106:107], v[80:81] op_sel_hi:[0,1]
	v_pk_mul_f32 v[82:83], v[106:107], v[82:83] op_sel_hi:[0,1]
	v_pk_mul_f32 v[76:77], v[106:107], v[76:77] op_sel_hi:[0,1]
	v_pk_mul_f32 v[78:79], v[106:107], v[78:79] op_sel_hi:[0,1]
	v_pk_mul_f32 v[84:85], v[106:107], v[84:85] op_sel_hi:[0,1]
	v_pk_mul_f32 v[86:87], v[106:107], v[86:87] op_sel_hi:[0,1]
	v_pk_mul_f32 v[92:93], v[106:107], v[92:93] op_sel_hi:[0,1]
	v_pk_mul_f32 v[94:95], v[106:107], v[94:95] op_sel_hi:[0,1]
	v_pk_mul_f32 v[88:89], v[106:107], v[88:89] op_sel_hi:[0,1]
	v_pk_mul_f32 v[90:91], v[106:107], v[90:91] op_sel_hi:[0,1]
	v_pk_fma_f32 v[70:71], v[2:3], v[70:71], v[10:11]
	v_pk_fma_f32 v[68:69], v[0:1], v[68:69], v[8:9]
	v_pk_fma_f32 v[66:67], v[6:7], v[66:67], v[14:15]
	v_pk_fma_f32 v[64:65], v[4:5], v[64:65], v[12:13]
	v_pk_fma_f32 v[74:75], v[18:19], v[74:75], v[26:27]
	v_pk_fma_f32 v[72:73], v[16:17], v[72:73], v[24:25]
	v_pk_fma_f32 v[82:83], v[22:23], v[82:83], v[30:31]
	v_pk_fma_f32 v[80:81], v[20:21], v[80:81], v[28:29]
	v_pk_fma_f32 v[78:79], v[34:35], v[78:79], v[42:43]
	v_pk_fma_f32 v[76:77], v[32:33], v[76:77], v[40:41]
	v_pk_fma_f32 v[86:87], v[38:39], v[86:87], v[46:47]
	v_pk_fma_f32 v[84:85], v[36:37], v[84:85], v[44:45]
	v_pk_fma_f32 v[94:95], v[50:51], v[94:95], v[58:59]
	v_pk_fma_f32 v[92:93], v[48:49], v[92:93], v[56:57]
	v_pk_fma_f32 v[90:91], v[54:55], v[90:91], v[62:63]
	v_pk_fma_f32 v[88:89], v[52:53], v[88:89], v[60:61]
	v_cvt_pk_bf16_f32 v68, v68, v69
	v_cvt_pk_bf16_f32 v69, v70, v71
	v_cvt_pk_bf16_f32 v64, v64, v65
	v_cvt_pk_bf16_f32 v65, v66, v67
	v_cvt_pk_bf16_f32 v66, v72, v73
	v_cvt_pk_bf16_f32 v67, v74, v75
	v_cvt_pk_bf16_f32 v70, v80, v81
	v_cvt_pk_bf16_f32 v71, v82, v83
	v_cvt_pk_bf16_f32 v72, v76, v77
	v_cvt_pk_bf16_f32 v73, v78, v79
	v_cvt_pk_bf16_f32 v74, v84, v85
	v_cvt_pk_bf16_f32 v75, v86, v87
	v_cvt_pk_bf16_f32 v76, v92, v93
	v_cvt_pk_bf16_f32 v77, v94, v95
	v_cvt_pk_bf16_f32 v78, v88, v89
	v_cvt_pk_bf16_f32 v79, v90, v91
	global_store_dwordx2 v[98:99], v[68:69], off offset:-2048
	global_store_dwordx2 v[98:99], v[64:65], off offset:-1536
	global_store_dwordx2 v[98:99], v[66:67], off offset:-1024
	global_store_dwordx2 v[98:99], v[70:71], off offset:-512
	global_store_dwordx2 v[98:99], v[72:73], off
	global_store_dwordx2 v[98:99], v[74:75], off offset:512
	global_store_dwordx2 v[98:99], v[76:77], off offset:1024
	global_store_dwordx2 v[98:99], v[78:79], off offset:1536
	v_lshl_add_u64 v[98:99], v[98:99], 0, s[10:11]
	s_cbranch_scc0 .LBB0_136

; __device__ __forceinline__ float wave_sum(float v) {
; #pragma unroll
;     for (int o = 1; o < 64; o <<= 1) v += __shfl_xor(v, o);
;     return v;
; }
; __global__ void __launch_bounds__(NWAVES * 64, 2) mk_fwd(Args args) {
;     ...
;         for (int m = gw; m < SEQ; m += NGW) {
;             const f32x4* xr = (const f32x4*)(XR + (size_t)m * DMODEL) + lane;
;             f32x4 v[8]; float s = 0.f;
; #pragma unroll
;             for (int j = 0; j < 8; ++j) { v[j] = xr[64 * j]; s += (v[j][0] * v[j][0] + v[j][1] * v[j][1]) + (v[j][2] * v[j][2] + v[j][3] * v[j][3]); }
;             const float rstd = __builtin_amdgcn_rsqf(wave_sum(s) * (1.f / DMODEL) + EPS);
;             f32x4* o = (f32x4*)(out_p + (size_t)m * DMODEL) + lane;
; #pragma unroll
;             for (int j = 0; j < 8; ++j) { const f32x4 g = *((const f32x4*)final_norm_w + lane + 64 * j); o[64 * j] = v[j] * rstd * g; }
;         }
.Lfn_nopf:
	v_mul_f32_e32 v81, v21, v21
	v_pk_mul_f32 v[58:59], v[26:27], v[26:27]
	v_pk_mul_f32 v[60:61], v[24:25], v[24:25]
	v_mul_f32_e32 v62, v29, v29
	v_mul_f32_e32 v64, v31, v31
	v_mov_b32_e32 v68, v33
	v_mov_b32_e32 v69, v37
	v_mov_b32_e32 v72, v35
	v_mov_b32_e32 v73, v39
	v_mul_f32_e32 v88, v50, v50
	v_mul_f32_e32 v89, v51, v51
	v_mov_b32_e32 v66, v32
	v_mov_b32_e32 v67, v36
	v_mov_b32_e32 v70, v34
	v_mov_b32_e32 v71, v38
	v_pk_mul_f32 v[74:75], v[42:43], v[42:43]
	v_pk_mul_f32 v[76:77], v[40:41], v[40:41]
	v_pk_mov_b32 v[82:83], v[60:61], v[58:59] op_sel:[1,0]
	v_mov_b32_e32 v61, v59
	v_pk_fma_f32 v[58:59], v[28:29], v[28:29], v[62:63] op_sel_hi:[1,1,0]
	v_pk_fma_f32 v[62:63], v[30:31], v[30:31], v[64:65] op_sel_hi:[1,1,0]
	v_pk_mul_f32 v[64:65], v[68:69], v[68:69]
	v_pk_mul_f32 v[68:69], v[72:73], v[72:73]
	v_pk_mov_b32 v[72:73], v[76:77], v[74:75] op_sel:[1,0]
	v_mov_b32_e32 v77, v75
	v_mov_b32_e32 v59, v88
	v_mov_b32_e32 v63, v89
	v_pk_fma_f32 v[64:65], v[66:67], v[66:67], v[64:65]
	v_pk_fma_f32 v[66:67], v[70:71], v[70:71], v[68:69]
	v_mul_f32_e32 v78, v45, v45
	v_mul_f32_e32 v80, v47, v47
	v_pk_add_f32 v[68:69], v[72:73], v[76:77]
	v_pk_add_f32 v[58:59], v[58:59], v[62:63]
	v_pk_add_f32 v[62:63], v[64:65], v[66:67]
	v_mul_f32_e32 v19, v20, v20
	v_mul_f32_e32 v84, v22, v22
	v_mul_f32_e32 v85, v23, v23
	v_pk_fma_f32 v[74:75], v[44:45], v[44:45], v[78:79] op_sel_hi:[1,1,0]
	v_pk_fma_f32 v[78:79], v[46:47], v[46:47], v[80:81] op_sel_hi:[1,1,0]
	v_pk_add_f32 v[64:65], v[68:69], v[68:69] op_sel:[0,1] op_sel_hi:[1,0]
	v_pk_add_f32 v[62:63], v[62:63], v[62:63] op_sel:[0,1] op_sel_hi:[1,0]
	v_mov_b32_e32 v75, v84
	v_mov_b32_e32 v79, v85
	v_mov_b32_e32 v65, v81
	v_mov_b32_e32 v63, v19
	v_pk_add_f32 v[66:67], v[74:75], v[78:79]
	v_pk_add_f32 v[62:63], v[62:63], v[64:65]
	v_pk_add_f32 v[60:61], v[82:83], v[60:61]
	v_pk_add_f32 v[62:63], v[62:63], v[66:67]
	v_mul_f32_e32 v86, v48, v48
	v_mul_f32_e32 v87, v49, v49
	v_pk_add_f32 v[60:61], v[60:61], v[60:61] op_sel:[0,1] op_sel_hi:[1,0]
	v_pk_add_f32 v[62:63], v[62:63], v[62:63] op_sel:[0,1] op_sel_hi:[1,0]
	v_mov_b32_e32 v61, v87
	v_mov_b32_e32 v63, v86
	v_pk_add_f32 v[60:61], v[62:63], v[60:61]
	s_nop 0
	v_pk_add_f32 v[58:59], v[60:61], v[58:59]
	s_nop 0
	v_add_f32_e32 v19, v58, v59
	s_waitcnt lgkmcnt(0)
	s_nop 1
	v_add_f32_dpp v19, v19, v19 quad_perm:[1,0,3,2] row_mask:0xf bank_mask:0xf
	s_nop 1
	v_add_f32_dpp v19, v19, v19 quad_perm:[2,3,0,1] row_mask:0xf bank_mask:0xf
	s_nop 1
	v_add_f32_dpp v19, v19, v19 row_half_mirror row_mask:0xf bank_mask:0xf
	s_nop 1
	v_add_f32_dpp v19, v19, v19 row_mirror row_mask:0xf bank_mask:0xf
	v_mov_b32_e32 v58, v19
	s_nop 1
	v_permlane16_swap_b32_e32 v19, v58
	v_add_f32_e32 v19, v19, v58
	v_mov_b32_e32 v58, v19
	s_nop 1
	v_permlane32_swap_b32_e32 v19, v58
	v_add_f32_e32 v19, v19, v58
	s_nop 0
	s_nop 0
	s_nop 0
	v_fmamk_f32 v19, v19, 0x3a000000, v18
	v_rsq_f32_e32 v58, v19
	s_nop 0
	v_pk_mul_f32 v[32:33], v[58:59], v[32:33] op_sel_hi:[0,1]
	v_pk_mul_f32 v[34:35], v[58:59], v[34:35] op_sel_hi:[0,1]
	v_pk_mul_f32 v[34:35], v[102:103], v[34:35]
	v_pk_mul_f32 v[32:33], v[100:101], v[32:33]
	global_store_dwordx4 v[56:57], v[32:35], off
	v_pk_mul_f32 v[38:39], v[58:59], v[38:39] op_sel_hi:[0,1]
	v_pk_mul_f32 v[36:37], v[58:59], v[36:37] op_sel_hi:[0,1]
	v_pk_mul_f32 v[22:23], v[58:59], v[22:23] op_sel_hi:[0,1]
	v_pk_mul_f32 v[20:21], v[58:59], v[20:21] op_sel_hi:[0,1]
	v_pk_mul_f32 v[26:27], v[58:59], v[26:27] op_sel_hi:[0,1]
	v_pk_mul_f32 v[24:25], v[58:59], v[24:25] op_sel_hi:[0,1]
	v_pk_mul_f32 v[32:33], v[104:105], v[36:37]
	v_pk_mul_f32 v[34:35], v[106:107], v[38:39]
	global_store_dwordx4 v[56:57], v[32:35], off offset:1024
	v_pk_mul_f32 v[36:37], v[58:59], v[42:43] op_sel_hi:[0,1]
	v_pk_mul_f32 v[38:39], v[58:59], v[40:41] op_sel_hi:[0,1]
	v_pk_mul_f32 v[32:33], v[108:109], v[38:39]
	v_pk_mul_f32 v[34:35], v[110:111], v[36:37]
	global_store_dwordx4 v[56:57], v[32:35], off offset:2048
	v_pk_mul_f32 v[36:37], v[58:59], v[46:47] op_sel_hi:[0,1]
	v_pk_mul_f32 v[38:39], v[58:59], v[44:45] op_sel_hi:[0,1]
	v_pk_mul_f32 v[32:33], v[112:113], v[38:39]
	v_pk_mul_f32 v[34:35], v[114:115], v[36:37]
	global_store_dwordx4 v[56:57], v[32:35], off offset:3072
	v_add_co_u32_e32 v36, vcc, s8, v56
	v_pk_mul_f32 v[20:21], v[116:117], v[20:21]
	v_addc_co_u32_e32 v37, vcc, 0, v57, vcc
	v_pk_mul_f32 v[22:23], v[118:119], v[22:23]
	global_store_dwordx4 v[36:37], v[20:23], off
	s_nop 1
	v_pk_mul_f32 v[20:21], v[120:121], v[24:25]
	v_pk_mul_f32 v[22:23], v[122:123], v[26:27]
	global_store_dwordx4 v[36:37], v[20:23], off offset:1024
	v_pk_mul_f32 v[24:25], v[58:59], v[30:31] op_sel_hi:[0,1]
	v_pk_mul_f32 v[26:27], v[58:59], v[28:29] op_sel_hi:[0,1]
	v_pk_mul_f32 v[20:21], v[124:125], v[26:27]
	v_pk_mul_f32 v[22:23], v[126:127], v[24:25]
	global_store_dwordx4 v[36:37], v[20:23], off offset:2048
	v_pk_mul_f32 v[24:25], v[58:59], v[50:51] op_sel_hi:[0,1]
	v_pk_mul_f32 v[26:27], v[58:59], v[48:49] op_sel_hi:[0,1]
	v_pk_mul_f32 v[20:21], v[128:129], v[26:27]
	v_pk_mul_f32 v[22:23], v[130:131], v[24:25]
	global_store_dwordx4 v[36:37], v[20:23], off offset:3072
	s_cbranch_scc1 .LBB0_885
